# gate columns of PROJ (read once, late, by the retention epilogue) stored non-temporal
# baseline (speedup 1.0000x reference)
; __device__ __forceinline__ unsigned cvt_pk_bf16(float lo, float hi) { unsigned r; asm volatile("v_cvt_pk_bf16_f32 %0, %1, %2" : "=v"(r) : "v"(lo), "v"(hi)); return r; }
;     __device__ __forceinline__ void operator()(const f32x4 (&acc)[2][2][4][2], const Unit& u, int wr, int wc, int fr, int fq) const {
;     ...
;             for (int m = 0; m < 4; ++m) { const int row = row0 + ai * HALF + m * 16; bf16_t* rowp = O + (size_t)row * ldc + col0;
;                 float sc = 1.f;
;                 if (mode) { const float e = (float)((row & 2047) - 1024) * lg; sc = (mode == 1) ? __builtin_amdgcn_exp2f(e) : __builtin_amdgcn_exp2f(-e) * 0.0625f; }
; #pragma unroll
;                 for (int bj = 0; bj < 2; ++bj) { const f32x4 v0 = acc[ai][bj][m][0] * sc, v1 = acc[ai][bj][m][1] * sc;
;                     u32x4 w; w.x = cvt_pk_bf16(v0[0], v0[1]); w.y = cvt_pk_bf16(v0[2], v0[3]); w.z = cvt_pk_bf16(v1[0], v1[1]); w.w = cvt_pk_bf16(v1[2], v1[3]);
;                     *(u32x4*)(rowp + bj * HALF) = w; } }
.Lp1_ep_plain:
	s_cmp_ge_u32 s18, 24
	s_cbranch_scc1 .Lp1_ep_plain_nt
	v_add_u32_e32 v205, 0x0, v204
	v_cvt_pk_bf16_f32 v212, v0, v1
	v_cvt_pk_bf16_f32 v213, v2, v3
	v_cvt_pk_bf16_f32 v214, v4, v5
	v_cvt_pk_bf16_f32 v215, v6, v7
	s_nop 1
	global_store_dwordx4 v205, v[212:215], s[50:51] offset:0
	s_nop 1
	v_cvt_pk_bf16_f32 v212, v32, v33
	v_cvt_pk_bf16_f32 v213, v34, v35
	v_cvt_pk_bf16_f32 v214, v36, v37
	v_cvt_pk_bf16_f32 v215, v38, v39
	s_nop 1
	global_store_dwordx4 v205, v[212:215], s[50:51] offset:256
	s_nop 1
	v_add_u32_e32 v205, 0x38000, v204
	v_cvt_pk_bf16_f32 v212, v8, v9
	v_cvt_pk_bf16_f32 v213, v10, v11
	v_cvt_pk_bf16_f32 v214, v12, v13
	v_cvt_pk_bf16_f32 v215, v14, v15
	s_nop 1
	global_store_dwordx4 v205, v[212:215], s[50:51] offset:0
	s_nop 1
	v_cvt_pk_bf16_f32 v212, v40, v41
	v_cvt_pk_bf16_f32 v213, v42, v43
	v_cvt_pk_bf16_f32 v214, v44, v45
	v_cvt_pk_bf16_f32 v215, v46, v47
	s_nop 1
	global_store_dwordx4 v205, v[212:215], s[50:51] offset:256
	s_nop 1
	v_add_u32_e32 v205, 0x70000, v204
	v_cvt_pk_bf16_f32 v212, v16, v17
	v_cvt_pk_bf16_f32 v213, v18, v19
	v_cvt_pk_bf16_f32 v214, v20, v21
	v_cvt_pk_bf16_f32 v215, v22, v23
	s_nop 1
	global_store_dwordx4 v205, v[212:215], s[50:51] offset:0
	s_nop 1
	v_cvt_pk_bf16_f32 v212, v48, v49
	v_cvt_pk_bf16_f32 v213, v50, v51
	v_cvt_pk_bf16_f32 v214, v52, v53
	v_cvt_pk_bf16_f32 v215, v54, v55
	s_nop 1
	global_store_dwordx4 v205, v[212:215], s[50:51] offset:256
	s_nop 1
	v_add_u32_e32 v205, 0xa8000, v204
	v_cvt_pk_bf16_f32 v212, v24, v25
	v_cvt_pk_bf16_f32 v213, v26, v27
	v_cvt_pk_bf16_f32 v214, v28, v29
	v_cvt_pk_bf16_f32 v215, v30, v31
	s_nop 1
	global_store_dwordx4 v205, v[212:215], s[50:51] offset:0
	s_nop 1
	v_cvt_pk_bf16_f32 v212, v56, v57
	v_cvt_pk_bf16_f32 v213, v58, v59
	v_cvt_pk_bf16_f32 v214, v60, v61
	v_cvt_pk_bf16_f32 v215, v62, v63
	s_nop 1
	global_store_dwordx4 v205, v[212:215], s[50:51] offset:256
	s_nop 1
	v_add_u32_e32 v205, 0x1c0000, v204
	v_cvt_pk_bf16_f32 v212, v64, v65
	v_cvt_pk_bf16_f32 v213, v66, v67
	v_cvt_pk_bf16_f32 v214, v68, v69
	v_cvt_pk_bf16_f32 v215, v70, v71
	s_nop 1
	global_store_dwordx4 v205, v[212:215], s[50:51] offset:0
	s_nop 1
	v_cvt_pk_bf16_f32 v212, v96, v97
	v_cvt_pk_bf16_f32 v213, v98, v99
	v_cvt_pk_bf16_f32 v214, v100, v101
	v_cvt_pk_bf16_f32 v215, v102, v103
	s_nop 1
	global_store_dwordx4 v205, v[212:215], s[50:51] offset:256
	s_nop 1
	v_add_u32_e32 v205, 0x1f8000, v204
	v_cvt_pk_bf16_f32 v212, v72, v73
	v_cvt_pk_bf16_f32 v213, v74, v75
	v_cvt_pk_bf16_f32 v214, v76, v77
	v_cvt_pk_bf16_f32 v215, v78, v79
	s_nop 1
	global_store_dwordx4 v205, v[212:215], s[50:51] offset:0
	s_nop 1
	v_cvt_pk_bf16_f32 v212, v104, v105
	v_cvt_pk_bf16_f32 v213, v106, v107
	v_cvt_pk_bf16_f32 v214, v108, v109
	v_cvt_pk_bf16_f32 v215, v110, v111
	s_nop 1
	global_store_dwordx4 v205, v[212:215], s[50:51] offset:256
	s_nop 1
	v_add_u32_e32 v205, 0x230000, v204
	v_cvt_pk_bf16_f32 v212, v80, v81
	v_cvt_pk_bf16_f32 v213, v82, v83
	v_cvt_pk_bf16_f32 v214, v84, v85
	v_cvt_pk_bf16_f32 v215, v86, v87
	s_nop 1
	global_store_dwordx4 v205, v[212:215], s[50:51] offset:0
	s_nop 1
	v_cvt_pk_bf16_f32 v212, v112, v113
	v_cvt_pk_bf16_f32 v213, v114, v115
	v_cvt_pk_bf16_f32 v214, v116, v117
	v_cvt_pk_bf16_f32 v215, v118, v119
	s_nop 1
	global_store_dwordx4 v205, v[212:215], s[50:51] offset:256
	s_nop 1
	v_add_u32_e32 v205, 0x268000, v204
	v_cvt_pk_bf16_f32 v212, v88, v89
	v_cvt_pk_bf16_f32 v213, v90, v91
	v_cvt_pk_bf16_f32 v214, v92, v93
	v_cvt_pk_bf16_f32 v215, v94, v95
	s_nop 1
	global_store_dwordx4 v205, v[212:215], s[50:51] offset:0
	s_nop 1
	v_cvt_pk_bf16_f32 v212, v120, v121
	v_cvt_pk_bf16_f32 v213, v122, v123
	v_cvt_pk_bf16_f32 v214, v124, v125
	v_cvt_pk_bf16_f32 v215, v126, v127
	s_nop 1
	global_store_dwordx4 v205, v[212:215], s[50:51] offset:256
	s_nop 1
	s_branch .Lp1_ep_done
; __device__ __forceinline__ unsigned cvt_pk_bf16(float lo, float hi) { unsigned r; asm volatile("v_cvt_pk_bf16_f32 %0, %1, %2" : "=v"(r) : "v"(lo), "v"(hi)); return r; }
;     __device__ __forceinline__ void operator()(const f32x4 (&acc)[2][2][4][2], const Unit& u, int wr, int wc, int fr, int fq) const {
;     ...
;             for (int m = 0; m < 4; ++m) { const int row = row0 + ai * HALF + m * 16; bf16_t* rowp = O + (size_t)row * ldc + col0;
;                 float sc = 1.f;
;                 if (mode) { const float e = (float)((row & 2047) - 1024) * lg; sc = (mode == 1) ? __builtin_amdgcn_exp2f(e) : __builtin_amdgcn_exp2f(-e) * 0.0625f; }
; #pragma unroll
;                 for (int bj = 0; bj < 2; ++bj) { const f32x4 v0 = acc[ai][bj][m][0] * sc, v1 = acc[ai][bj][m][1] * sc;
;                     u32x4 w; w.x = cvt_pk_bf16(v0[0], v0[1]); w.y = cvt_pk_bf16(v0[2], v0[3]); w.z = cvt_pk_bf16(v1[0], v1[1]); w.w = cvt_pk_bf16(v1[2], v1[3]);
;                     *(u32x4*)(rowp + bj * HALF) = w; } }
.Lp1_ep_plain_nt:
	v_add_u32_e32 v205, 0x0, v204
	v_cvt_pk_bf16_f32 v212, v0, v1
	v_cvt_pk_bf16_f32 v213, v2, v3
	v_cvt_pk_bf16_f32 v214, v4, v5
	v_cvt_pk_bf16_f32 v215, v6, v7
	s_nop 1
	global_store_dwordx4 v205, v[212:215], s[50:51] offset:0 nt
	s_nop 1
	v_cvt_pk_bf16_f32 v212, v32, v33
	v_cvt_pk_bf16_f32 v213, v34, v35
	v_cvt_pk_bf16_f32 v214, v36, v37
	v_cvt_pk_bf16_f32 v215, v38, v39
	s_nop 1
	global_store_dwordx4 v205, v[212:215], s[50:51] offset:256 nt
	s_nop 1
	v_add_u32_e32 v205, 0x38000, v204
	v_cvt_pk_bf16_f32 v212, v8, v9
	v_cvt_pk_bf16_f32 v213, v10, v11
	v_cvt_pk_bf16_f32 v214, v12, v13
	v_cvt_pk_bf16_f32 v215, v14, v15
	s_nop 1
	global_store_dwordx4 v205, v[212:215], s[50:51] offset:0 nt
	s_nop 1
	v_cvt_pk_bf16_f32 v212, v40, v41
	v_cvt_pk_bf16_f32 v213, v42, v43
	v_cvt_pk_bf16_f32 v214, v44, v45
	v_cvt_pk_bf16_f32 v215, v46, v47
	s_nop 1
	global_store_dwordx4 v205, v[212:215], s[50:51] offset:256 nt
	s_nop 1
	v_add_u32_e32 v205, 0x70000, v204
	v_cvt_pk_bf16_f32 v212, v16, v17
	v_cvt_pk_bf16_f32 v213, v18, v19
	v_cvt_pk_bf16_f32 v214, v20, v21
	v_cvt_pk_bf16_f32 v215, v22, v23
	s_nop 1
	global_store_dwordx4 v205, v[212:215], s[50:51] offset:0 nt
	s_nop 1
	v_cvt_pk_bf16_f32 v212, v48, v49
	v_cvt_pk_bf16_f32 v213, v50, v51
	v_cvt_pk_bf16_f32 v214, v52, v53
	v_cvt_pk_bf16_f32 v215, v54, v55
	s_nop 1
	global_store_dwordx4 v205, v[212:215], s[50:51] offset:256 nt
	s_nop 1
	v_add_u32_e32 v205, 0xa8000, v204
	v_cvt_pk_bf16_f32 v212, v24, v25
	v_cvt_pk_bf16_f32 v213, v26, v27
	v_cvt_pk_bf16_f32 v214, v28, v29
	v_cvt_pk_bf16_f32 v215, v30, v31
	s_nop 1
	global_store_dwordx4 v205, v[212:215], s[50:51] offset:0 nt
	s_nop 1
	v_cvt_pk_bf16_f32 v212, v56, v57
	v_cvt_pk_bf16_f32 v213, v58, v59
	v_cvt_pk_bf16_f32 v214, v60, v61
	v_cvt_pk_bf16_f32 v215, v62, v63
	s_nop 1
	global_store_dwordx4 v205, v[212:215], s[50:51] offset:256 nt
	s_nop 1
	v_add_u32_e32 v205, 0x1c0000, v204
	v_cvt_pk_bf16_f32 v212, v64, v65
	v_cvt_pk_bf16_f32 v213, v66, v67
	v_cvt_pk_bf16_f32 v214, v68, v69
	v_cvt_pk_bf16_f32 v215, v70, v71
	s_nop 1
	global_store_dwordx4 v205, v[212:215], s[50:51] offset:0 nt
	s_nop 1
	v_cvt_pk_bf16_f32 v212, v96, v97
	v_cvt_pk_bf16_f32 v213, v98, v99
	v_cvt_pk_bf16_f32 v214, v100, v101
	v_cvt_pk_bf16_f32 v215, v102, v103
	s_nop 1
	global_store_dwordx4 v205, v[212:215], s[50:51] offset:256 nt
	s_nop 1
	v_add_u32_e32 v205, 0x1f8000, v204
	v_cvt_pk_bf16_f32 v212, v72, v73
	v_cvt_pk_bf16_f32 v213, v74, v75
	v_cvt_pk_bf16_f32 v214, v76, v77
	v_cvt_pk_bf16_f32 v215, v78, v79
	s_nop 1
	global_store_dwordx4 v205, v[212:215], s[50:51] offset:0 nt
	s_nop 1
	v_cvt_pk_bf16_f32 v212, v104, v105
	v_cvt_pk_bf16_f32 v213, v106, v107
	v_cvt_pk_bf16_f32 v214, v108, v109
	v_cvt_pk_bf16_f32 v215, v110, v111
	s_nop 1
	global_store_dwordx4 v205, v[212:215], s[50:51] offset:256 nt
	s_nop 1
	v_add_u32_e32 v205, 0x230000, v204
	v_cvt_pk_bf16_f32 v212, v80, v81
	v_cvt_pk_bf16_f32 v213, v82, v83
	v_cvt_pk_bf16_f32 v214, v84, v85
	v_cvt_pk_bf16_f32 v215, v86, v87
	s_nop 1
	global_store_dwordx4 v205, v[212:215], s[50:51] offset:0 nt
	s_nop 1
	v_cvt_pk_bf16_f32 v212, v112, v113
	v_cvt_pk_bf16_f32 v213, v114, v115
	v_cvt_pk_bf16_f32 v214, v116, v117
	v_cvt_pk_bf16_f32 v215, v118, v119
	s_nop 1
	global_store_dwordx4 v205, v[212:215], s[50:51] offset:256 nt
	s_nop 1
	v_add_u32_e32 v205, 0x268000, v204
	v_cvt_pk_bf16_f32 v212, v88, v89
	v_cvt_pk_bf16_f32 v213, v90, v91
	v_cvt_pk_bf16_f32 v214, v92, v93
	v_cvt_pk_bf16_f32 v215, v94, v95
	s_nop 1
	global_store_dwordx4 v205, v[212:215], s[50:51] offset:0 nt
	s_nop 1
	v_cvt_pk_bf16_f32 v212, v120, v121
	v_cvt_pk_bf16_f32 v213, v122, v123
	v_cvt_pk_bf16_f32 v214, v124, v125
	v_cvt_pk_bf16_f32 v215, v126, v127
	s_nop 1
	global_store_dwordx4 v205, v[212:215], s[50:51] offset:256 nt
	s_nop 1
